# NSA selected-branch tile loop: tile-list entries carried in registers and prefetched two tiles ahead (removes two exposed LDS round trips per tile)
# speedup vs baseline: 1.0093x; 1.0093x over previous
; template <int MODE> ...
;     ...
;   ALOAD(0);
;   ASTORE(0);
;   __syncthreads();
;   for (int it = 0; it < nt; ++it) {
;     if (it + 1 < nt) ALOAD(it + 1);
;     const int key0 = KEY0_OF(it);
; DI void nsa_item(const Params& p, int l_, int item, char* lds, int dry) {
;     ...
;   const u64 U = wuni[0] | wuni[1] | wuni[2] | wuni[3];
;   if (w == 0 && ((U >> lane) & 1ull)) tlist[__popcll(U & ((1ull << lane) - 1ull))] = lane;
;   const int ntl = __popcll(U);
;   selb[0] = selm[r];
;   selb[1] = selm[32 + r];
;   __syncthreads();
;   attn_init(O, m, l);
;   attn_run<M_SLC>(lds, zb + KSC + g * 64, zb + VSC + g * 64, ZS, nullptr, ntl, 0, qf, O, m, l, qpos, cq, selb, linv, wq0);
.LBB0_724:
	s_or_b64 exec, exec, s[0:1]
	v_lshlrev_b32_e32 v0, 3, v157
	v_add_u32_e32 v0, 0xd000, v0
	v_mov_b32_e32 v4, v209
	ds_read2_b64 v[144:147], v0 offset0:96 offset1:128
	s_waitcnt lgkmcnt(0)
	s_barrier
	ds_read_b32 v0, v1 offset:54592
	v_readlane_b32 s0, v254, 17
	s_lshl_b32 s0, s0, 7
	v_readlane_b32 s2, v254, 18
	v_readlane_b32 s3, v254, 19
	s_add_u32 s2, s2, s0
	v_ashrrev_i32_e32 v181, 3, v4
	s_addc_u32 s3, s3, 0
	s_waitcnt lgkmcnt(0)
	v_lshl_add_u32 v0, v0, 6, v181
	s_movk_i32 s4, 0x1980
	v_lshlrev_b32_e32 v5, 3, v4
	s_add_u32 s0, s2, 0x1e00
	v_mul_lo_u32 v0, v0, s4
	v_and_b32_e32 v182, 56, v5
	s_addc_u32 s1, s3, 0
	v_or_b32_e32 v0, v0, v182
	s_add_u32 s2, s2, 0x1f00
	v_add_u32_e32 v6, 0x33000, v0
	v_mov_b32_e32 v7, v1
	s_addc_u32 s3, s3, 0
	v_lshlrev_b64 v[8:9], 1, v[0:1]
	v_lshlrev_b64 v[6:7], 1, v[6:7]
	v_lshl_add_u64 v[10:11], s[0:1], 0, v[8:9]
	v_lshl_add_u64 v[12:13], s[0:1], 0, v[6:7]
	v_lshl_add_u64 v[8:9], s[2:3], 0, v[8:9]
	v_lshl_add_u64 v[6:7], s[2:3], 0, v[6:7]
	global_load_dwordx4 v[148:151], v[10:11], off
	global_load_dwordx4 v[152:155], v[12:13], off
	global_load_dwordx4 v[156:159], v[8:9], off
	global_load_dwordx4 v[160:163], v[6:7], off
	v_cmp_eq_u64_e32 vcc, 0, v[2:3]
	v_mul_lo_u32 v0, v181, s76
	v_readlane_b32 s60, v253, 49
	v_lshl_add_u32 v183, v182, 1, v0
	s_and_b64 vcc, exec, vcc
	v_readlane_b32 s61, v253, 50
	v_readlane_b32 s62, v253, 51
	v_readlane_b32 s63, v253, 52
	v_readlane_b32 s64, v253, 53
	v_readlane_b32 s65, v253, 54
	v_readlane_b32 s66, v253, 55
	v_readlane_b32 s67, v253, 56
	v_readlane_b32 s68, v253, 57
	v_readlane_b32 s69, v253, 58
	v_readlane_b32 s70, v253, 59
	v_readlane_b32 s71, v253, 60
	v_readlane_b32 s72, v253, 61
	v_readlane_b32 s73, v253, 62
	v_readlane_b32 s74, v253, 63
	v_readlane_b32 s75, v254, 0
	s_waitcnt vmcnt(3)
	ds_write_b128 v183, v[148:151]
	s_waitcnt vmcnt(1)
	ds_write_b128 v183, v[156:159] offset:18432
	ds_write_b128 v183, v[152:155] offset:4608
	s_waitcnt vmcnt(0)
	ds_write_b128 v183, v[160:163] offset:23040
	s_waitcnt lgkmcnt(0)
	s_barrier
	s_cbranch_vccnz .LBB0_747
	v_bcnt_u32_b32 v0, v2, 0
	v_bcnt_u32_b32 v184, v3, v0
	v_and_b32_e32 v185, 31, v4
	v_and_b32_e32 v0, 16, v4
	v_lshrrev_b32_e32 v2, 2, v4
	v_and_b32_e32 v3, 63, v4
	v_bfe_u32 v4, v4, 5, 1
	v_lshlrev_b32_e32 v188, 2, v4
	v_lshlrev_b32_e32 v3, 2, v3
	v_and_or_b32 v189, v2, 3, v188
	v_and_b32_e32 v2, 24, v5
	v_mov_b32_e32 v14, v1
	v_mov_b32_e32 v15, v1
	v_lshlrev_b32_e32 v186, 4, v4
	v_xor_b32_e32 v187, 0x80, v3
	v_lshl_or_b32 v190, v0, 1, v2
	v_mov_b32_e32 v0, v1
	v_mov_b32_e32 v2, v1
	v_mov_b32_e32 v3, v1
	v_mov_b32_e32 v4, v1
	v_mov_b32_e32 v5, v1
	v_mov_b32_e32 v6, v1
	v_mov_b32_e32 v7, v1
	v_mov_b32_e32 v8, v1
	v_mov_b32_e32 v9, v1
	v_mov_b32_e32 v10, v1
	v_mov_b32_e32 v11, v1
	v_mov_b32_e32 v12, v1
	v_mov_b32_e32 v13, v1
	v_mov_b64_e32 v[30:31], v[14:15]
	v_mov_b64_e32 v[62:63], v[14:15]
	v_mov_b64_e32 v[46:47], v[14:15]
	v_mov_b64_e32 v[78:79], v[14:15]
	s_or_b32 s14, s77, 63
	v_add_u32_e32 v191, 30, v178
	v_add_u32_e32 v192, 29, v178
	v_add_u32_e32 v193, 24, v178
	v_add_u32_e32 v194, 23, v178
	v_add_u32_e32 v195, 22, v178
	v_add_u32_e32 v196, 21, v178
	v_add_u32_e32 v197, 16, v178
	v_add_u32_e32 v198, 15, v178
	v_add_u32_e32 v199, 14, v178
	v_add_u32_e32 v200, 13, v178
	v_add_u32_e32 v201, 8, v178
	v_add_u32_e32 v202, 7, v178
	v_add_u32_e32 v203, 6, v178
	v_add_u32_e32 v204, 5, v178
	s_mov_b32 s4, 0
	v_mov_b32_e32 v205, 0xf149f2ca
	v_mov_b32_e32 v180, 0
	v_mov_b64_e32 v[28:29], v[12:13]
	v_mov_b64_e32 v[26:27], v[10:11]
	v_mov_b64_e32 v[24:25], v[8:9]
	v_mov_b64_e32 v[22:23], v[6:7]
	v_mov_b64_e32 v[20:21], v[4:5]
	v_mov_b64_e32 v[18:19], v[2:3]
	v_mov_b64_e32 v[16:17], v[0:1]
	v_mov_b64_e32 v[60:61], v[12:13]
	v_mov_b64_e32 v[58:59], v[10:11]
	v_mov_b64_e32 v[56:57], v[8:9]
	v_mov_b64_e32 v[54:55], v[6:7]
	v_mov_b64_e32 v[52:53], v[4:5]
	v_mov_b64_e32 v[50:51], v[2:3]
	v_mov_b64_e32 v[48:49], v[0:1]
	v_mov_b64_e32 v[44:45], v[12:13]
	v_mov_b64_e32 v[42:43], v[10:11]
	v_mov_b64_e32 v[40:41], v[8:9]
	v_mov_b64_e32 v[38:39], v[6:7]
	v_mov_b64_e32 v[36:37], v[4:5]
	v_mov_b64_e32 v[34:35], v[2:3]
	v_mov_b64_e32 v[32:33], v[0:1]
	v_mov_b64_e32 v[76:77], v[12:13]
	v_mov_b64_e32 v[74:75], v[10:11]
	v_mov_b64_e32 v[72:73], v[8:9]
	v_mov_b64_e32 v[70:71], v[6:7]
	v_mov_b64_e32 v[68:69], v[4:5]
	v_mov_b64_e32 v[66:67], v[2:3]
	v_mov_b64_e32 v[64:65], v[0:1]
	v_mov_b32_e32 v80, 0
	v_mov_b32_e32 v15, 0xf149f2ca
	v_mov_b32_e32 v14, 0
	s_movk_i32 s54, 0x1980
	s_lshl_b32 s5, s4, 2
	v_mov_b32_e32 v0, s5
	ds_read_b32 v246, v0 offset:54592
	ds_read_b32 v245, v0 offset:54596
	ds_read_b32 v247, v0 offset:54600
	s_waitcnt lgkmcnt(0)
	s_add_i32 s15, s4, 1
	v_cmp_ge_u32_e32 vcc, s15, v184
	s_cbranch_vccnz .LBB0_728
	s_branch .LBB0_727
.LBB0_726:
	v_mov_b32_e32 v246, v245
	v_mov_b32_e32 v245, v247
	s_mov_b32 s4, s15
	s_add_i32 s15, s4, 1
	v_cmp_ge_u32_e32 vcc, s15, v184
	s_cbranch_vccnz .LBB0_728
.LBB0_727:
	s_lshl_b32 s5, s4, 2
	v_mov_b32_e32 v0, s5
	ds_read_b32 v247, v0 offset:54600
	v_mov_b32_e32 v3, v1
	v_lshl_add_u32 v0, v245, 6, v181
	v_mul_lo_u32 v0, v0, s54
	v_or_b32_e32 v0, v0, v182
	v_add_u32_e32 v2, 0x33000, v0
	v_lshlrev_b64 v[4:5], 1, v[0:1]
	v_lshl_add_u64 v[6:7], s[0:1], 0, v[4:5]
	v_lshlrev_b64 v[2:3], 1, v[2:3]
	v_lshl_add_u64 v[4:5], s[2:3], 0, v[4:5]
	v_lshl_add_u64 v[8:9], s[0:1], 0, v[2:3]
	global_load_dwordx4 v[148:151], v[6:7], off
	global_load_dwordx4 v[152:155], v[8:9], off
	v_lshl_add_u64 v[2:3], s[2:3], 0, v[2:3]
	global_load_dwordx4 v[156:159], v[4:5], off
	global_load_dwordx4 v[160:163], v[2:3], off
.LBB0_728:
	v_mov_b32_e32 v2, v246
	s_lshl_b32 s4, s4, 6
	s_and_b32 s4, s4, 64
	s_mulk_i32 s4, 0x90
	v_cmp_lt_u32_e64 s[42:43], s15, v184
	v_readfirstlane_b32 s5, v2
	v_lshlrev_b64 v[2:3], v2, 1
	v_and_b32_e32 v5, v3, v145
	v_and_b32_e32 v4, v2, v144
	v_and_b32_e32 v3, v3, v147
	v_and_b32_e32 v2, v2, v146
	s_lshl_b32 s16, s5, 6
	v_or_b32_e32 v0, s4, v186
	v_or_b32_e32 v206, s4, v190
	v_cmp_ne_u64_e64 s[4:5], 0, v[4:5]
	v_cmp_ne_u64_e64 s[6:7], 0, v[2:3]
	s_mov_b32 s17, 0
	s_mov_b64 s[8:9], -1
	s_branch .LBB0_731
